# m3 + attention T5-bias add batched 5 reads per full LDS drain (no counted lgkmcnt), 4 round trips instead of 16
# baseline (speedup 1.0000x reference)
.LBB0_2974:
	v_add_u32_e32 v183, s36, v234
	ds_read_b64_tr_b16 v[178:179], v183 offset:24576
	ds_read_b64_tr_b16 v[180:181], v183 offset:25088
	s_waitcnt lgkmcnt(9)
	v_mfma_f32_32x32x16_bf16 v[98:113], v[82:85], v[130:133], v[2:17]
	v_add_f32_e32 v86, v66, v67
	v_add_f32_e32 v86, v68, v86
	v_add_f32_e32 v86, v69, v86
	v_add_f32_e32 v86, v70, v86
	v_add_f32_e32 v86, v71, v86
	v_cvt_pk_bf16_f32 v142, v66, v67
	v_cvt_pk_bf16_f32 v143, v68, v69
	ds_read_b64_tr_b16 v[174:175], v183 offset:28672
	ds_read_b64_tr_b16 v[176:177], v183 offset:29184
	v_add_f32_e32 v66, v72, v86
	s_waitcnt lgkmcnt(10)
	v_mfma_f32_32x32x16_bf16 v[82:97], v[166:169], v[130:133], v[2:17]
	v_add_f32_e32 v66, v73, v66
	v_add_f32_e32 v66, v74, v66
	v_add_f32_e32 v66, v75, v66
	v_cvt_pk_bf16_f32 v144, v70, v71
	v_cvt_pk_bf16_f32 v145, v72, v73
	ds_read_b64_tr_b16 v[166:167], v183 offset:25600
	ds_read_b64_tr_b16 v[168:169], v183 offset:26112
	s_waitcnt lgkmcnt(11)
	v_mfma_f32_32x32x16_bf16 v[98:113], v[170:173], v[126:129], v[98:113]
	v_add_f32_e32 v66, v76, v66
	v_add_f32_e32 v66, v77, v66
	v_add_f32_e32 v66, v78, v66
	v_add_f32_e32 v66, v79, v66
	v_cvt_pk_bf16_f32 v138, v74, v75
	v_cvt_pk_bf16_f32 v139, v76, v77
	ds_read_b64_tr_b16 v[74:75], v183 offset:29696
	ds_read_b64_tr_b16 v[76:77], v183 offset:30208
	s_waitcnt lgkmcnt(12)
	v_mfma_f32_32x32x16_bf16 v[82:97], v[158:161], v[126:129], v[82:97]
	v_add_f32_e32 v66, v80, v66
	v_add_f32_e32 v66, v81, v66
	v_add_f32_e32 v66, v50, v66
	v_add_f32_e32 v66, v51, v66
	v_cvt_pk_bf16_f32 v140, v78, v79
	v_cvt_pk_bf16_f32 v141, v80, v81
	ds_read_b64_tr_b16 v[70:71], v183 offset:26624
	ds_read_b64_tr_b16 v[72:73], v183 offset:27136
	s_waitcnt lgkmcnt(13)
	v_mfma_f32_32x32x16_bf16 v[98:113], v[162:165], v[118:121], v[98:113]
	v_add_f32_e32 v66, v52, v66
	v_add_f32_e32 v66, v53, v66
	v_add_f32_e32 v66, v54, v66
	v_add_f32_e32 v78, v55, v66
	v_cvt_pk_bf16_f32 v134, v50, v51
	v_cvt_pk_bf16_f32 v135, v52, v53
	ds_read_b64_tr_b16 v[66:67], v183 offset:30720
	ds_read_b64_tr_b16 v[68:69], v183 offset:31232
	s_waitcnt lgkmcnt(14)
	v_mfma_f32_32x32x16_bf16 v[82:97], v[150:153], v[118:121], v[82:97]
	v_add_f32_e32 v50, v56, v78
	v_add_f32_e32 v50, v57, v50
	v_add_f32_e32 v50, v58, v50
	v_add_f32_e32 v50, v59, v50
	v_cvt_pk_bf16_f32 v136, v54, v55
	v_cvt_pk_bf16_f32 v137, v56, v57
	ds_read_b64_tr_b16 v[54:55], v183 offset:27648
	ds_read_b64_tr_b16 v[56:57], v183 offset:28160
	s_waitcnt lgkmcnt(14)
	v_mfma_f32_32x32x16_bf16 v[98:113], v[154:157], v[114:117], v[98:113]
	v_add_f32_e32 v50, v60, v50
	v_add_f32_e32 v50, v61, v50
	v_add_f32_e32 v50, v62, v50
	v_add_f32_e32 v78, v63, v50
	v_cvt_pk_bf16_f32 v122, v58, v59
	v_cvt_pk_bf16_f32 v123, v60, v61
	ds_read_b64_tr_b16 v[50:51], v183 offset:31744
	ds_read_b64_tr_b16 v[52:53], v183 offset:32256
	v_mfma_f32_32x32x16_bf16 v[82:97], v[146:149], v[114:117], v[82:97]
	v_add_f32_e32 v58, v64, v78
	v_add_f32_e32 v58, v65, v58
	v_add_f32_e32 v58, 0, v58
	v_cvt_pk_bf16_f32 v124, v62, v63
	v_cvt_pk_bf16_f32 v125, v64, v65
	v_lshl_add_u64 v[216:217], v[210:211], 0, s[82:83]
	s_mov_b64 s[0:1], 0x7440000
	v_lshl_add_u64 v[60:61], v[216:217], 0, s[0:1]
	s_add_i32 s0, s35, s21
	s_mov_b32 s1, m0
	s_mov_b32 m0, s0
	s_nop 0
	global_load_lds_dwordx4 v[60:61], off
	s_mov_b32 m0, s1
	v_lshl_add_u64 v[218:219], v[214:215], 0, s[82:83]
	s_mov_b64 s[0:1], 0x8420000
	v_lshl_add_u64 v[60:61], v[218:219], 0, s[0:1]
	s_add_i32 s0, s24, s18
	s_mov_b32 s1, m0
	s_mov_b32 m0, s0
	s_nop 0
	global_load_lds_dwordx4 v[60:61], off
	s_mov_b32 m0, s1
	s_cmp_le_i32 s29, s17
	s_cbranch_scc1 .LBB0_2976
	ds_read2_b32 v[60:61], v188 offset0:122 offset1:123
	ds_read2_b32 v[240:241], v188 offset0:90 offset1:91
	ds_read2_b32 v[242:243], v188 offset0:120 offset1:121
	ds_read2_b32 v[244:245], v188 offset0:88 offset1:89
	ds_read2_b32 v[248:249], v188 offset0:114 offset1:115
	s_waitcnt lgkmcnt(0)
	v_pk_add_f32 v[98:99], v[98:99], v[60:61] op_sel:[0,1] op_sel_hi:[1,0]
	v_pk_add_f32 v[82:83], v[82:83], v[240:241] op_sel:[0,1] op_sel_hi:[1,0]
	v_pk_add_f32 v[100:101], v[100:101], v[242:243] op_sel:[0,1] op_sel_hi:[1,0]
	v_pk_add_f32 v[84:85], v[84:85], v[244:245] op_sel:[0,1] op_sel_hi:[1,0]
	v_pk_add_f32 v[102:103], v[102:103], v[248:249] op_sel:[0,1] op_sel_hi:[1,0]
	ds_read2_b32 v[60:61], v188 offset0:82 offset1:83
	ds_read2_b32 v[240:241], v188 offset0:112 offset1:113
	ds_read2_b32 v[242:243], v188 offset0:80 offset1:81
	ds_read2_b32 v[244:245], v188 offset0:106 offset1:107
	ds_read2_b32 v[248:249], v188 offset0:74 offset1:75
	s_waitcnt lgkmcnt(0)
	v_pk_add_f32 v[86:87], v[86:87], v[60:61] op_sel:[0,1] op_sel_hi:[1,0]
	v_pk_add_f32 v[104:105], v[104:105], v[240:241] op_sel:[0,1] op_sel_hi:[1,0]
	v_pk_add_f32 v[88:89], v[88:89], v[242:243] op_sel:[0,1] op_sel_hi:[1,0]
	v_pk_add_f32 v[106:107], v[106:107], v[244:245] op_sel:[0,1] op_sel_hi:[1,0]
	v_pk_add_f32 v[90:91], v[90:91], v[248:249] op_sel:[0,1] op_sel_hi:[1,0]
	ds_read2_b32 v[60:61], v188 offset0:104 offset1:105
	ds_read2_b32 v[240:241], v188 offset0:72 offset1:73
	ds_read2_b32 v[242:243], v188 offset0:98 offset1:99
	ds_read2_b32 v[244:245], v188 offset0:66 offset1:67
	ds_read2_b32 v[248:249], v188 offset0:96 offset1:97
	s_waitcnt lgkmcnt(0)
	v_pk_add_f32 v[108:109], v[108:109], v[60:61] op_sel:[0,1] op_sel_hi:[1,0]
	v_pk_add_f32 v[92:93], v[92:93], v[240:241] op_sel:[0,1] op_sel_hi:[1,0]
	v_pk_add_f32 v[110:111], v[110:111], v[242:243] op_sel:[0,1] op_sel_hi:[1,0]
	v_pk_add_f32 v[94:95], v[94:95], v[244:245] op_sel:[0,1] op_sel_hi:[1,0]
	v_pk_add_f32 v[112:113], v[112:113], v[248:249] op_sel:[0,1] op_sel_hi:[1,0]
	ds_read2_b32 v[60:61], v188 offset0:64 offset1:65
	s_waitcnt lgkmcnt(0)
	v_pk_add_f32 v[96:97], v[96:97], v[60:61] op_sel:[0,1] op_sel_hi:[1,0]

.LBB0_2979:
	s_add_i32 s0, s24, 0x2000
	s_cmpk_lg_i32 s24, 0x4000
	s_cselect_b32 s25, s0, 0
	v_add_u32_e32 v238, s35, v234
	ds_read_b64_tr_b16 v[158:159], v238 offset:24576
	ds_read_b64_tr_b16 v[160:161], v238 offset:25088
	s_waitcnt lgkmcnt(9)
	v_mfma_f32_32x32x16_bf16 v[66:81], v[58:61], v[130:133], v[2:17]
	v_add_f32_e32 v50, v98, v99
	v_add_f32_e32 v50, v100, v50
	v_add_f32_e32 v50, v101, v50
	v_add_f32_e32 v50, v102, v50
	v_add_f32_e32 v50, v103, v50
	v_cvt_pk_bf16_f32 v142, v98, v99
	v_cvt_pk_bf16_f32 v143, v100, v101
	ds_read_b64_tr_b16 v[154:155], v238 offset:28672
	ds_read_b64_tr_b16 v[156:157], v238 offset:29184
	v_add_f32_e32 v50, v104, v50
	v_add_f32_e32 v50, v105, v50
	v_add_f32_e32 v50, v106, v50
	v_add_f32_e32 v98, v107, v50
	s_waitcnt lgkmcnt(10)
	v_mfma_f32_32x32x16_bf16 v[50:65], v[146:149], v[130:133], v[2:17]
	v_cvt_pk_bf16_f32 v144, v102, v103
	v_cvt_pk_bf16_f32 v145, v104, v105
	ds_read_b64_tr_b16 v[150:151], v238 offset:25600
	ds_read_b64_tr_b16 v[152:153], v238 offset:26112
	s_waitcnt lgkmcnt(11)
	v_mfma_f32_32x32x16_bf16 v[66:81], v[174:177], v[126:129], v[66:81]
	v_add_f32_e32 v98, v108, v98
	v_add_f32_e32 v98, v109, v98
	v_add_f32_e32 v98, v110, v98
	v_add_f32_e32 v98, v111, v98
	v_cvt_pk_bf16_f32 v138, v106, v107
	v_cvt_pk_bf16_f32 v139, v108, v109
	ds_read_b64_tr_b16 v[146:147], v238 offset:29696
	ds_read_b64_tr_b16 v[148:149], v238 offset:30208
	s_waitcnt lgkmcnt(12)
	v_mfma_f32_32x32x16_bf16 v[50:65], v[162:165], v[126:129], v[50:65]
	v_add_f32_e32 v98, v112, v98
	v_add_f32_e32 v98, v113, v98
	v_add_f32_e32 v98, v82, v98
	v_add_f32_e32 v98, v83, v98
	v_cvt_pk_bf16_f32 v140, v110, v111
	v_cvt_pk_bf16_f32 v141, v112, v113
	ds_read_b64_tr_b16 v[106:107], v238 offset:26624
	ds_read_b64_tr_b16 v[108:109], v238 offset:27136
	s_waitcnt lgkmcnt(13)
	v_mfma_f32_32x32x16_bf16 v[66:81], v[178:181], v[118:121], v[66:81]
	v_add_f32_e32 v98, v84, v98
	v_add_f32_e32 v98, v85, v98
	v_add_f32_e32 v98, v86, v98
	v_add_f32_e32 v98, v87, v98
	v_cvt_pk_bf16_f32 v134, v82, v83
	v_cvt_pk_bf16_f32 v135, v84, v85
	ds_read_b64_tr_b16 v[102:103], v238 offset:30720
	ds_read_b64_tr_b16 v[104:105], v238 offset:31232
	s_waitcnt lgkmcnt(14)
	v_mfma_f32_32x32x16_bf16 v[50:65], v[166:169], v[118:121], v[50:65]
	v_add_f32_e32 v82, v88, v98
	v_add_f32_e32 v82, v89, v82
	v_add_f32_e32 v82, v90, v82
	v_add_f32_e32 v82, v91, v82
	v_cvt_pk_bf16_f32 v136, v86, v87
	v_cvt_pk_bf16_f32 v137, v88, v89
	ds_read_b64_tr_b16 v[98:99], v238 offset:27648
	ds_read_b64_tr_b16 v[100:101], v238 offset:28160
	s_waitcnt lgkmcnt(14)
	v_mfma_f32_32x32x16_bf16 v[66:81], v[182:185], v[114:117], v[66:81]
	v_add_f32_e32 v82, v92, v82
	v_add_f32_e32 v82, v93, v82
	v_add_f32_e32 v82, v94, v82
	v_add_f32_e32 v82, v95, v82
	v_cvt_pk_bf16_f32 v122, v90, v91
	v_cvt_pk_bf16_f32 v123, v92, v93
	ds_read_b64_tr_b16 v[86:87], v238 offset:31744
	ds_read_b64_tr_b16 v[88:89], v238 offset:32256
	v_mfma_f32_32x32x16_bf16 v[50:65], v[170:173], v[114:117], v[50:65]
	v_add_f32_e32 v82, v96, v82
	v_add_f32_e32 v82, v97, v82
	v_add_f32_e32 v82, 0, v82
	v_cvt_pk_bf16_f32 v124, v94, v95
	v_cvt_pk_bf16_f32 v125, v96, v97
	s_mov_b64 s[0:1], 0x7450000
	v_lshl_add_u64 v[84:85], v[216:217], 0, s[0:1]
	s_add_i32 s0, s24, s21
	s_mov_b32 s1, m0
	s_mov_b32 m0, s0
	s_nop 0
	global_load_lds_dwordx4 v[84:85], off
	s_mov_b32 m0, s1
	s_mov_b64 s[0:1], 0x8430000
	v_lshl_add_u64 v[84:85], v[218:219], 0, s[0:1]
	s_add_i32 s0, s25, s18
	s_add_i32 s1, s29, 64
	s_cmp_le_i32 s1, s17
	s_mov_b32 s1, m0
	s_mov_b32 m0, s0
	s_nop 0
	global_load_lds_dwordx4 v[84:85], off
	s_mov_b32 m0, s1
	s_cbranch_scc1 .LBB0_2981
	ds_read2_b32 v[84:85], v188 offset0:58 offset1:59
	ds_read2_b32 v[240:241], v188 offset0:26 offset1:27
	ds_read2_b32 v[242:243], v188 offset0:56 offset1:57
	ds_read2_b32 v[244:245], v188 offset0:24 offset1:25
	ds_read2_b32 v[248:249], v188 offset0:50 offset1:51
	s_waitcnt lgkmcnt(0)
	v_pk_add_f32 v[66:67], v[66:67], v[84:85] op_sel:[0,1] op_sel_hi:[1,0]
	v_pk_add_f32 v[50:51], v[50:51], v[240:241] op_sel:[0,1] op_sel_hi:[1,0]
	v_pk_add_f32 v[68:69], v[68:69], v[242:243] op_sel:[0,1] op_sel_hi:[1,0]
	v_pk_add_f32 v[52:53], v[52:53], v[244:245] op_sel:[0,1] op_sel_hi:[1,0]
	v_pk_add_f32 v[70:71], v[70:71], v[248:249] op_sel:[0,1] op_sel_hi:[1,0]
	ds_read2_b32 v[84:85], v188 offset0:18 offset1:19
	ds_read2_b32 v[240:241], v188 offset0:48 offset1:49
	ds_read2_b32 v[242:243], v188 offset0:16 offset1:17
	ds_read2_b32 v[244:245], v188 offset0:42 offset1:43
	ds_read2_b32 v[248:249], v188 offset0:10 offset1:11
	s_waitcnt lgkmcnt(0)
	v_pk_add_f32 v[54:55], v[54:55], v[84:85] op_sel:[0,1] op_sel_hi:[1,0]
	v_pk_add_f32 v[72:73], v[72:73], v[240:241] op_sel:[0,1] op_sel_hi:[1,0]
	v_pk_add_f32 v[56:57], v[56:57], v[242:243] op_sel:[0,1] op_sel_hi:[1,0]
	v_pk_add_f32 v[74:75], v[74:75], v[244:245] op_sel:[0,1] op_sel_hi:[1,0]
	v_pk_add_f32 v[58:59], v[58:59], v[248:249] op_sel:[0,1] op_sel_hi:[1,0]
	ds_read2_b32 v[84:85], v188 offset0:40 offset1:41
	ds_read2_b32 v[240:241], v188 offset0:8 offset1:9
	ds_read2_b32 v[242:243], v188 offset0:34 offset1:35
	ds_read2_b32 v[244:245], v188 offset0:2 offset1:3
	ds_read2_b32 v[248:249], v188 offset0:32 offset1:33
	s_waitcnt lgkmcnt(0)
	v_pk_add_f32 v[76:77], v[76:77], v[84:85] op_sel:[0,1] op_sel_hi:[1,0]
	v_pk_add_f32 v[60:61], v[60:61], v[240:241] op_sel:[0,1] op_sel_hi:[1,0]
	v_pk_add_f32 v[78:79], v[78:79], v[242:243] op_sel:[0,1] op_sel_hi:[1,0]
	v_pk_add_f32 v[62:63], v[62:63], v[244:245] op_sel:[0,1] op_sel_hi:[1,0]
	v_pk_add_f32 v[80:81], v[80:81], v[248:249] op_sel:[0,1] op_sel_hi:[1,0]
	ds_read2_b32 v[84:85], v188 offset1:1
	s_waitcnt lgkmcnt(0)
	v_pk_add_f32 v[64:65], v[64:65], v[84:85] op_sel:[0,1] op_sel_hi:[1,0]
